# static priority mirror: one s_setprio 1 for waves 0-3 per GEMM unit, flips deleted
# baseline (speedup 1.0000x reference)
.LBB0_271:
	s_ashr_i32 s63, s62, 31
	s_lshl_b64 s[0:1], s[62:63], 20
	s_add_u32 s66, s49, s0
	s_addc_u32 s67, s82, s1
	s_and_b64 s[0:1], s[4:5], exec
	s_cselect_b32 s0, s67, s75
	s_cselect_b32 s1, s66, s74
	s_ashr_i32 s65, s64, 31
	s_lshl_b64 s[68:69], s[64:65], 20
	s_add_u32 s68, s45, s68
	s_addc_u32 s69, s47, s69
	s_and_b64 s[78:79], s[4:5], exec
	s_cselect_b32 s3, s69, s77
	s_cselect_b32 s63, s68, s76
	s_add_u32 s74, s74, 0x80080
	s_addc_u32 s75, s75, 0
	s_add_u32 s65, s76, 0x100
	s_addc_u32 s71, s77, 0
	s_mov_b32 s90, -2
	s_waitcnt vmcnt(0)
	s_cmp_ge_u32 s97, 0x100
	s_cbranch_scc1 .Lkprio_0
	s_setprio 1

.LBB0_542:
	s_ashr_i32 s35, s34, 31
	s_lshl_b64 s[0:1], s[34:35], 20
	s_add_u32 s36, s29, s0
	s_addc_u32 s37, s30, s1
	s_and_b64 s[0:1], s[6:7], exec
	s_cselect_b32 s0, s37, s43
	s_cselect_b32 s1, s36, s42
	s_ashr_i32 s25, s24, 31
	s_lshl_b64 s[38:39], s[24:25], 20
	s_add_u32 s38, s27, s38
	s_addc_u32 s39, s28, s39
	s_and_b64 s[46:47], s[6:7], exec
	s_cselect_b32 s3, s39, s45
	s_cselect_b32 s9, s38, s44
	s_add_u32 s42, s42, 0x80080
	s_addc_u32 s43, s43, 0
	s_add_u32 s25, s44, 0x100
	s_addc_u32 s35, s45, 0
	s_mov_b32 s58, -2
	s_waitcnt lgkmcnt(0)
	s_waitcnt vmcnt(0)
	s_cmp_ge_u32 s97, 0x100
	s_cbranch_scc1 .Lkprio_1
	s_setprio 1

.LBB0_635:
	s_ashr_i32 s67, s66, 31
	s_lshl_b64 s[12:13], s[66:67], 20
	s_add_u32 s70, s55, s12
	s_addc_u32 s71, s57, s13
	s_and_b64 s[6:7], s[6:7], exec
	s_cselect_b32 s1, s71, s11
	s_cselect_b32 s3, s70, s10
	s_add_u32 s6, s8, 0x80080
	s_addc_u32 s7, s9, 0
	s_add_u32 s12, s10, 0x100
	s_addc_u32 s13, s11, 0
	s_mov_b32 s15, -2
	s_waitcnt vmcnt(0)
	s_cmp_ge_u32 s97, 0x100
	s_cbranch_scc1 .Lkprio_2
	s_setprio 1

.LBB0_875:
	s_mov_b32 s1, -2
	s_mov_b64 s[4:5], s[22:23]
	s_cmp_ge_u32 s97, 0x100
	s_cbranch_scc1 .Lkprio_3
	s_setprio 1
